# v32 = v30 + MT2 k-loops (w_out, mlp2): each staging set gets its own counted ladder vmcnt(15..8) so the other set's loads stay in flight (prefetch distance 2 k-tiles)
# baseline (speedup 1.0000x reference)
.LBB0_834:
	ds_read_b128 v[176:179], v207
	ds_read_b128 v[144:147], v207 offset:32
	ds_read_b128 v[184:187], v208 offset:18432
	ds_read_b128 v[148:151], v208 offset:18464
	ds_read_b128 v[180:183], v207 offset:4608
	ds_read_b128 v[156:159], v207 offset:4640
	ds_read_b128 v[188:191], v208 offset:23040
	ds_read_b128 v[164:167], v208 offset:23072
	ds_read_b128 v[152:155], v207 offset:64
	ds_read_b128 v[128:131], v207 offset:96
	ds_read_b128 v[160:163], v207 offset:4672
	ds_read_b128 v[136:139], v207 offset:4704
	ds_read_b128 v[168:171], v208 offset:18496
	ds_read_b128 v[132:135], v208 offset:18528
	ds_read_b128 v[172:175], v208 offset:23104
	ds_read_b128 v[140:143], v208 offset:23136
	s_cmp_lt_u32 s19, 13
	s_waitcnt lgkmcnt(0)
	s_barrier
	s_cbranch_scc0 .Lmt2_last_0
	s_waitcnt vmcnt(15)
	ds_write_b128 v206, v[64:67]
	s_waitcnt vmcnt(14)
	ds_write_b128 v206, v[68:71] offset:4608
	s_waitcnt vmcnt(13)
	ds_write_b128 v206, v[72:75] offset:9216
	s_waitcnt vmcnt(12)
	ds_write_b128 v206, v[76:79] offset:13824
	s_waitcnt vmcnt(11)
	ds_write_b128 v206, v[88:91] offset:18432
	s_waitcnt vmcnt(10)
	ds_write_b128 v206, v[96:99] offset:23040
	s_waitcnt vmcnt(9)
	ds_write_b128 v206, v[104:107] offset:27648
	s_waitcnt vmcnt(8)
	ds_write_b128 v206, v[108:111] offset:32256
	s_cbranch_scc0 .LBB0_836
	v_lshl_add_u64 v[72:73], s[12:13], 0, v[200:201]
	v_add_co_u32_e32 v64, vcc, 0x2957000, v72
	v_lshl_add_u64 v[104:105], s[10:11], 0, v[200:201]
	s_nop 0
	v_addc_co_u32_e32 v65, vcc, 0, v73, vcc
	v_add_co_u32_e32 v68, vcc, 0x2967000, v72
	s_nop 1
	v_addc_co_u32_e32 v69, vcc, 0, v73, vcc
	v_add_co_u32_e32 v74, vcc, 0x2977000, v72
	global_load_dwordx4 v[64:67], v[64:65], off offset:2688
	s_nop 0
	global_load_dwordx4 v[68:71], v[68:69], off offset:2688
	v_addc_co_u32_e32 v75, vcc, 0, v73, vcc
	v_add_co_u32_e32 v76, vcc, 0x2987000, v72
	s_nop 1
	v_addc_co_u32_e32 v77, vcc, 0, v73, vcc
	v_add_co_u32_e32 v88, vcc, 0x4c0000, v104
	global_load_dwordx4 v[72:75], v[74:75], off offset:2688
	s_nop 0
	global_load_dwordx4 v[76:79], v[76:77], off offset:2688
	v_addc_co_u32_e32 v89, vcc, 0, v105, vcc
	v_add_co_u32_e32 v96, vcc, 0x4d0000, v104
	s_nop 1
	v_addc_co_u32_e32 v97, vcc, 0, v105, vcc
	v_add_co_u32_e32 v106, vcc, 0x4e0000, v104
	global_load_dwordx4 v[88:91], v[88:89], off offset:384
	s_nop 0
	global_load_dwordx4 v[96:99], v[96:97], off offset:384
	v_addc_co_u32_e32 v107, vcc, 0, v105, vcc
	v_add_co_u32_e32 v108, vcc, 0x4f0000, v104
	s_nop 1
	v_addc_co_u32_e32 v109, vcc, 0, v105, vcc
	global_load_dwordx4 v[104:107], v[106:107], off offset:384
	s_nop 0
	global_load_dwordx4 v[108:111], v[108:109], off offset:384
.LBB0_836:
	v_mfma_f32_32x32x16_bf16 v[48:63], v[176:179], v[184:187], v[48:63]
	s_waitcnt lgkmcnt(0)
	s_barrier
	s_cmp_gt_u32 s19, 13
	s_cselect_b64 s[16:17], -1, 0
	s_and_b64 vcc, exec, s[16:17]
	v_mfma_f32_32x32x16_bf16 v[16:31], v[176:179], v[188:191], v[16:31]
	v_mfma_f32_32x32x16_bf16 v[32:47], v[180:183], v[184:187], v[32:47]
	v_mfma_f32_32x32x16_bf16 v[0:15], v[180:183], v[188:191], v[0:15]
	v_mfma_f32_32x32x16_bf16 v[48:63], v[144:147], v[148:151], v[48:63]
	v_mfma_f32_32x32x16_bf16 v[16:31], v[144:147], v[164:167], v[16:31]
	v_mfma_f32_32x32x16_bf16 v[32:47], v[156:159], v[148:151], v[32:47]
	v_mfma_f32_32x32x16_bf16 v[0:15], v[156:159], v[164:167], v[0:15]
	v_mfma_f32_32x32x16_bf16 v[48:63], v[152:155], v[168:171], v[48:63]
	v_mfma_f32_32x32x16_bf16 v[16:31], v[152:155], v[172:175], v[16:31]
	v_mfma_f32_32x32x16_bf16 v[32:47], v[160:163], v[168:171], v[32:47]
	v_mfma_f32_32x32x16_bf16 v[0:15], v[160:163], v[172:175], v[0:15]
	ds_read_b128 v[176:179], v207
	ds_read_b128 v[152:155], v207 offset:32
	ds_read_b128 v[188:191], v208 offset:18432
	ds_read_b128 v[156:159], v208 offset:18464
	ds_read_b128 v[184:187], v207 offset:4608
	ds_read_b128 v[160:163], v207 offset:4640
	v_mfma_f32_32x32x16_bf16 v[48:63], v[128:131], v[132:135], v[48:63]
	v_mfma_f32_32x32x16_bf16 v[16:31], v[128:131], v[140:143], v[16:31]
	ds_read_b128 v[196:199], v208 offset:23040
	ds_read_b128 v[172:175], v208 offset:23072
	ds_read_b128 v[164:167], v207 offset:64
	ds_read_b128 v[148:151], v207 offset:96
	ds_read_b128 v[168:171], v207 offset:4672
	ds_read_b128 v[128:131], v207 offset:4704
	ds_read_b128 v[180:183], v208 offset:18496
	ds_read_b128 v[144:147], v208 offset:18528
	v_mfma_f32_32x32x16_bf16 v[32:47], v[136:139], v[132:135], v[32:47]
	ds_read_b128 v[192:195], v208 offset:23104
	ds_read_b128 v[132:135], v208 offset:23136
	s_waitcnt lgkmcnt(0)
	s_barrier
	v_mfma_f32_32x32x16_bf16 v[0:15], v[136:139], v[140:143], v[0:15]
	s_cbranch_vccnz .LBB0_833
	s_cmp_gt_u32 s19, 11
	s_waitcnt vmcnt(15)
	ds_write_b128 v206, v[80:83]
	s_waitcnt vmcnt(14)
	ds_write_b128 v206, v[84:87] offset:4608
	s_waitcnt vmcnt(13)
	ds_write_b128 v206, v[92:95] offset:9216
	s_waitcnt vmcnt(12)
	ds_write_b128 v206, v[100:103] offset:13824
	s_waitcnt vmcnt(11)
	ds_write_b128 v206, v[112:115] offset:18432
	s_waitcnt vmcnt(10)
	ds_write_b128 v206, v[116:119] offset:23040
	s_waitcnt vmcnt(9)
	ds_write_b128 v206, v[120:123] offset:27648
	s_waitcnt vmcnt(8)
	ds_write_b128 v206, v[124:127] offset:32256
	s_cbranch_scc1 .LBB0_833
	v_lshl_add_u64 v[92:93], s[12:13], 0, v[200:201]
	v_add_co_u32_e32 v80, vcc, 0x2957000, v92
	v_lshl_add_u64 v[120:121], s[10:11], 0, v[200:201]
	s_nop 0
	v_addc_co_u32_e32 v81, vcc, 0, v93, vcc
	v_add_co_u32_e32 v84, vcc, 0x2967000, v92
	s_nop 1
	v_addc_co_u32_e32 v85, vcc, 0, v93, vcc
	v_add_co_u32_e32 v94, vcc, 0x2977000, v92
	global_load_dwordx4 v[80:83], v[80:81], off offset:2816
	s_nop 0
	global_load_dwordx4 v[84:87], v[84:85], off offset:2816
	v_addc_co_u32_e32 v95, vcc, 0, v93, vcc
	v_add_co_u32_e32 v100, vcc, 0x2987000, v92
	s_nop 1
	v_addc_co_u32_e32 v101, vcc, 0, v93, vcc
	v_add_co_u32_e32 v112, vcc, 0x4c0000, v120
	global_load_dwordx4 v[92:95], v[94:95], off offset:2816
	s_nop 0
	global_load_dwordx4 v[100:103], v[100:101], off offset:2816
	v_addc_co_u32_e32 v113, vcc, 0, v121, vcc
	v_add_co_u32_e32 v116, vcc, 0x4d0000, v120
	s_nop 1
	v_addc_co_u32_e32 v117, vcc, 0, v121, vcc
	v_add_co_u32_e32 v122, vcc, 0x4e0000, v120
	global_load_dwordx4 v[112:115], v[112:113], off offset:512
	s_nop 0
	global_load_dwordx4 v[116:119], v[116:117], off offset:512
	v_addc_co_u32_e32 v123, vcc, 0, v121, vcc
	v_add_co_u32_e32 v124, vcc, 0x4f0000, v120
	s_nop 1
	v_addc_co_u32_e32 v125, vcc, 0, v121, vcc
	global_load_dwordx4 v[120:123], v[122:123], off offset:512
	s_nop 0
	global_load_dwordx4 v[124:127], v[124:125], off offset:512
	s_branch .LBB0_833
.Lmt2_last_0:
	s_waitcnt vmcnt(7)
	ds_write_b128 v206, v[64:67]
	s_waitcnt vmcnt(6)
	ds_write_b128 v206, v[68:71] offset:4608
	s_waitcnt vmcnt(5)
	ds_write_b128 v206, v[72:75] offset:9216
	s_waitcnt vmcnt(4)
	ds_write_b128 v206, v[76:79] offset:13824
	s_waitcnt vmcnt(3)
	ds_write_b128 v206, v[88:91] offset:18432
	s_waitcnt vmcnt(2)
	ds_write_b128 v206, v[96:99] offset:23040
	s_waitcnt vmcnt(1)
	ds_write_b128 v206, v[104:107] offset:27648
	s_waitcnt vmcnt(0)
	ds_write_b128 v206, v[108:111] offset:32256
	s_branch .LBB0_836

.LBB0_1067:
	ds_read_b128 v[176:179], v207
	ds_read_b128 v[144:147], v207 offset:32
	ds_read_b128 v[184:187], v208 offset:18432
	ds_read_b128 v[148:151], v208 offset:18464
	ds_read_b128 v[180:183], v207 offset:4608
	ds_read_b128 v[156:159], v207 offset:4640
	ds_read_b128 v[188:191], v208 offset:23040
	ds_read_b128 v[164:167], v208 offset:23072
	ds_read_b128 v[152:155], v207 offset:64
	ds_read_b128 v[128:131], v207 offset:96
	ds_read_b128 v[160:163], v207 offset:4672
	ds_read_b128 v[136:139], v207 offset:4704
	ds_read_b128 v[168:171], v208 offset:18496
	ds_read_b128 v[132:135], v208 offset:18528
	ds_read_b128 v[172:175], v208 offset:23104
	ds_read_b128 v[140:143], v208 offset:23136
	s_cmp_lt_u32 s19, 61
	s_waitcnt lgkmcnt(0)
	s_barrier
	s_cbranch_scc0 .Lmt2_last_1
	s_waitcnt vmcnt(15)
	ds_write_b128 v206, v[64:67]
	s_waitcnt vmcnt(14)
	ds_write_b128 v206, v[68:71] offset:4608
	s_waitcnt vmcnt(13)
	ds_write_b128 v206, v[72:75] offset:9216
	s_waitcnt vmcnt(12)
	ds_write_b128 v206, v[76:79] offset:13824
	s_waitcnt vmcnt(11)
	ds_write_b128 v206, v[88:91] offset:18432
	s_waitcnt vmcnt(10)
	ds_write_b128 v206, v[96:99] offset:23040
	s_waitcnt vmcnt(9)
	ds_write_b128 v206, v[104:107] offset:27648
	s_waitcnt vmcnt(8)
	ds_write_b128 v206, v[108:111] offset:32256
	s_cbranch_scc0 .LBB0_1069
	v_lshl_add_u64 v[72:73], s[12:13], 0, v[200:201]
	v_add_co_u32_e32 v64, vcc, 0x7157000, v72
	v_lshl_add_u64 v[104:105], s[10:11], 0, v[200:201]
	s_nop 0
	v_addc_co_u32_e32 v65, vcc, 0, v73, vcc
	v_add_co_u32_e32 v68, vcc, 0x7197000, v72
	s_nop 1
	v_addc_co_u32_e32 v69, vcc, 0, v73, vcc
	v_add_co_u32_e32 v74, vcc, 0x71d7000, v72
	global_load_dwordx4 v[64:67], v[64:65], off offset:2688
	s_nop 0
	global_load_dwordx4 v[68:71], v[68:69], off offset:2688
	v_addc_co_u32_e32 v75, vcc, 0, v73, vcc
	v_add_co_u32_e32 v76, vcc, 0x7217000, v72
	s_nop 1
	v_addc_co_u32_e32 v77, vcc, 0, v73, vcc
	v_add_co_u32_e32 v88, vcc, 0xec0000, v104
	global_load_dwordx4 v[72:75], v[74:75], off offset:2688
	s_nop 0
	global_load_dwordx4 v[76:79], v[76:77], off offset:2688
	v_addc_co_u32_e32 v89, vcc, 0, v105, vcc
	v_add_co_u32_e32 v96, vcc, 0xf00000, v104
	s_nop 1
	v_addc_co_u32_e32 v97, vcc, 0, v105, vcc
	v_add_co_u32_e32 v106, vcc, 0xf40000, v104
	global_load_dwordx4 v[88:91], v[88:89], off offset:384
	s_nop 0
	global_load_dwordx4 v[96:99], v[96:97], off offset:384
	v_addc_co_u32_e32 v107, vcc, 0, v105, vcc
	v_add_co_u32_e32 v108, vcc, 0xf80000, v104
	s_nop 1
	v_addc_co_u32_e32 v109, vcc, 0, v105, vcc
	global_load_dwordx4 v[104:107], v[106:107], off offset:384
	s_nop 0
	global_load_dwordx4 v[108:111], v[108:109], off offset:384
.LBB0_1069:
	v_mfma_f32_32x32x16_bf16 v[48:63], v[176:179], v[184:187], v[48:63]
	s_waitcnt lgkmcnt(0)
	s_barrier
	s_cmp_gt_u32 s19, 61
	s_cselect_b64 s[16:17], -1, 0
	s_and_b64 vcc, exec, s[16:17]
	v_mfma_f32_32x32x16_bf16 v[16:31], v[176:179], v[188:191], v[16:31]
	v_mfma_f32_32x32x16_bf16 v[32:47], v[180:183], v[184:187], v[32:47]
	v_mfma_f32_32x32x16_bf16 v[0:15], v[180:183], v[188:191], v[0:15]
	v_mfma_f32_32x32x16_bf16 v[48:63], v[144:147], v[148:151], v[48:63]
	v_mfma_f32_32x32x16_bf16 v[16:31], v[144:147], v[164:167], v[16:31]
	v_mfma_f32_32x32x16_bf16 v[32:47], v[156:159], v[148:151], v[32:47]
	v_mfma_f32_32x32x16_bf16 v[0:15], v[156:159], v[164:167], v[0:15]
	v_mfma_f32_32x32x16_bf16 v[48:63], v[152:155], v[168:171], v[48:63]
	v_mfma_f32_32x32x16_bf16 v[16:31], v[152:155], v[172:175], v[16:31]
	v_mfma_f32_32x32x16_bf16 v[32:47], v[160:163], v[168:171], v[32:47]
	v_mfma_f32_32x32x16_bf16 v[0:15], v[160:163], v[172:175], v[0:15]
	ds_read_b128 v[176:179], v207
	ds_read_b128 v[152:155], v207 offset:32
	ds_read_b128 v[188:191], v208 offset:18432
	ds_read_b128 v[156:159], v208 offset:18464
	ds_read_b128 v[184:187], v207 offset:4608
	ds_read_b128 v[160:163], v207 offset:4640
	v_mfma_f32_32x32x16_bf16 v[48:63], v[128:131], v[132:135], v[48:63]
	v_mfma_f32_32x32x16_bf16 v[16:31], v[128:131], v[140:143], v[16:31]
	ds_read_b128 v[196:199], v208 offset:23040
	ds_read_b128 v[172:175], v208 offset:23072
	ds_read_b128 v[164:167], v207 offset:64
	ds_read_b128 v[148:151], v207 offset:96
	ds_read_b128 v[168:171], v207 offset:4672
	ds_read_b128 v[128:131], v207 offset:4704
	ds_read_b128 v[180:183], v208 offset:18496
	ds_read_b128 v[144:147], v208 offset:18528
	v_mfma_f32_32x32x16_bf16 v[32:47], v[136:139], v[132:135], v[32:47]
	ds_read_b128 v[192:195], v208 offset:23104
	ds_read_b128 v[132:135], v208 offset:23136
	s_waitcnt lgkmcnt(0)
	s_barrier
	v_mfma_f32_32x32x16_bf16 v[0:15], v[136:139], v[140:143], v[0:15]
	s_cbranch_vccnz .LBB0_1066
	s_cmp_gt_u32 s19, 59
	s_waitcnt vmcnt(15)
	ds_write_b128 v206, v[80:83]
	s_waitcnt vmcnt(14)
	ds_write_b128 v206, v[84:87] offset:4608
	s_waitcnt vmcnt(13)
	ds_write_b128 v206, v[92:95] offset:9216
	s_waitcnt vmcnt(12)
	ds_write_b128 v206, v[100:103] offset:13824
	s_waitcnt vmcnt(11)
	ds_write_b128 v206, v[112:115] offset:18432
	s_waitcnt vmcnt(10)
	ds_write_b128 v206, v[116:119] offset:23040
	s_waitcnt vmcnt(9)
	ds_write_b128 v206, v[120:123] offset:27648
	s_waitcnt vmcnt(8)
	ds_write_b128 v206, v[124:127] offset:32256
	s_cbranch_scc1 .LBB0_1066
	v_lshl_add_u64 v[92:93], s[12:13], 0, v[200:201]
	v_add_co_u32_e32 v80, vcc, 0x7157000, v92
	v_lshl_add_u64 v[120:121], s[10:11], 0, v[200:201]
	s_nop 0
	v_addc_co_u32_e32 v81, vcc, 0, v93, vcc
	v_add_co_u32_e32 v84, vcc, 0x7197000, v92
	s_nop 1
	v_addc_co_u32_e32 v85, vcc, 0, v93, vcc
	v_add_co_u32_e32 v94, vcc, 0x71d7000, v92
	global_load_dwordx4 v[80:83], v[80:81], off offset:2816
	s_nop 0
	global_load_dwordx4 v[84:87], v[84:85], off offset:2816
	v_addc_co_u32_e32 v95, vcc, 0, v93, vcc
	v_add_co_u32_e32 v100, vcc, 0x7217000, v92
	s_nop 1
	v_addc_co_u32_e32 v101, vcc, 0, v93, vcc
	v_add_co_u32_e32 v112, vcc, 0xec0000, v120
	global_load_dwordx4 v[92:95], v[94:95], off offset:2816
	s_nop 0
	global_load_dwordx4 v[100:103], v[100:101], off offset:2816
	v_addc_co_u32_e32 v113, vcc, 0, v121, vcc
	v_add_co_u32_e32 v116, vcc, 0xf00000, v120
	s_nop 1
	v_addc_co_u32_e32 v117, vcc, 0, v121, vcc
	v_add_co_u32_e32 v122, vcc, 0xf40000, v120
	global_load_dwordx4 v[112:115], v[112:113], off offset:512
	s_nop 0
	global_load_dwordx4 v[116:119], v[116:117], off offset:512
	v_addc_co_u32_e32 v123, vcc, 0, v121, vcc
	v_add_co_u32_e32 v124, vcc, 0xf80000, v120
	s_nop 1
	v_addc_co_u32_e32 v125, vcc, 0, v121, vcc
	global_load_dwordx4 v[120:123], v[122:123], off offset:512
	s_nop 0
	global_load_dwordx4 v[124:127], v[124:125], off offset:512
	s_branch .LBB0_1066

.LBB0_2047:
	ds_read_b128 v[176:179], v207
	ds_read_b128 v[144:147], v207 offset:32
	ds_read_b128 v[184:187], v208 offset:18432
	ds_read_b128 v[148:151], v208 offset:18464
	ds_read_b128 v[180:183], v207 offset:4608
	ds_read_b128 v[156:159], v207 offset:4640
	ds_read_b128 v[188:191], v208 offset:23040
	ds_read_b128 v[164:167], v208 offset:23072
	ds_read_b128 v[152:155], v207 offset:64
	ds_read_b128 v[128:131], v207 offset:96
	ds_read_b128 v[160:163], v207 offset:4672
	ds_read_b128 v[136:139], v207 offset:4704
	ds_read_b128 v[168:171], v208 offset:18496
	ds_read_b128 v[132:135], v208 offset:18528
	ds_read_b128 v[172:175], v208 offset:23104
	ds_read_b128 v[140:143], v208 offset:23136
	s_cmp_lt_u32 s17, 61
	s_waitcnt lgkmcnt(0)
	s_barrier
	s_cbranch_scc0 .Lmt2_last_3
	s_waitcnt vmcnt(15)
	ds_write_b128 v206, v[64:67]
	s_waitcnt vmcnt(14)
	ds_write_b128 v206, v[68:71] offset:4608
	s_waitcnt vmcnt(13)
	ds_write_b128 v206, v[72:75] offset:9216
	s_waitcnt vmcnt(12)
	ds_write_b128 v206, v[76:79] offset:13824
	s_waitcnt vmcnt(11)
	ds_write_b128 v206, v[88:91] offset:18432
	s_waitcnt vmcnt(10)
	ds_write_b128 v206, v[96:99] offset:23040
	s_waitcnt vmcnt(9)
	ds_write_b128 v206, v[104:107] offset:27648
	s_waitcnt vmcnt(8)
	ds_write_b128 v206, v[108:111] offset:32256
	s_cbranch_scc0 .LBB0_2049
	v_lshl_add_u64 v[72:73], s[12:13], 0, v[200:201]
	v_add_co_u32_e32 v64, vcc, 0x7157000, v72
	v_lshl_add_u64 v[104:105], s[10:11], 0, v[200:201]
	s_nop 0
	v_addc_co_u32_e32 v65, vcc, 0, v73, vcc
	v_add_co_u32_e32 v68, vcc, 0x7197000, v72
	s_nop 1
	v_addc_co_u32_e32 v69, vcc, 0, v73, vcc
	v_add_co_u32_e32 v74, vcc, 0x71d7000, v72
	global_load_dwordx4 v[64:67], v[64:65], off offset:2688
	s_nop 0
	global_load_dwordx4 v[68:71], v[68:69], off offset:2688
	v_addc_co_u32_e32 v75, vcc, 0, v73, vcc
	v_add_co_u32_e32 v76, vcc, 0x7217000, v72
	s_nop 1
	v_addc_co_u32_e32 v77, vcc, 0, v73, vcc
	v_add_co_u32_e32 v88, vcc, 0xec0000, v104
	global_load_dwordx4 v[72:75], v[74:75], off offset:2688
	s_nop 0
	global_load_dwordx4 v[76:79], v[76:77], off offset:2688
	v_addc_co_u32_e32 v89, vcc, 0, v105, vcc
	v_add_co_u32_e32 v96, vcc, 0xf00000, v104
	s_nop 1
	v_addc_co_u32_e32 v97, vcc, 0, v105, vcc
	v_add_co_u32_e32 v106, vcc, 0xf40000, v104
	global_load_dwordx4 v[88:91], v[88:89], off offset:384
	s_nop 0
	global_load_dwordx4 v[96:99], v[96:97], off offset:384
	v_addc_co_u32_e32 v107, vcc, 0, v105, vcc
	v_add_co_u32_e32 v108, vcc, 0xf80000, v104
	s_nop 1
	v_addc_co_u32_e32 v109, vcc, 0, v105, vcc
	global_load_dwordx4 v[104:107], v[106:107], off offset:384
	s_nop 0
	global_load_dwordx4 v[108:111], v[108:109], off offset:384
.LBB0_2049:
	v_mfma_f32_32x32x16_bf16 v[48:63], v[176:179], v[184:187], v[48:63]
	s_waitcnt lgkmcnt(0)
	s_barrier
	s_cmp_gt_u32 s17, 61
	s_cselect_b64 s[14:15], -1, 0
	s_and_b64 vcc, exec, s[14:15]
	v_mfma_f32_32x32x16_bf16 v[16:31], v[176:179], v[188:191], v[16:31]
	v_mfma_f32_32x32x16_bf16 v[32:47], v[180:183], v[184:187], v[32:47]
	v_mfma_f32_32x32x16_bf16 v[0:15], v[180:183], v[188:191], v[0:15]
	v_mfma_f32_32x32x16_bf16 v[48:63], v[144:147], v[148:151], v[48:63]
	v_mfma_f32_32x32x16_bf16 v[16:31], v[144:147], v[164:167], v[16:31]
	v_mfma_f32_32x32x16_bf16 v[32:47], v[156:159], v[148:151], v[32:47]
	v_mfma_f32_32x32x16_bf16 v[0:15], v[156:159], v[164:167], v[0:15]
	v_mfma_f32_32x32x16_bf16 v[48:63], v[152:155], v[168:171], v[48:63]
	v_mfma_f32_32x32x16_bf16 v[16:31], v[152:155], v[172:175], v[16:31]
	v_mfma_f32_32x32x16_bf16 v[32:47], v[160:163], v[168:171], v[32:47]
	v_mfma_f32_32x32x16_bf16 v[0:15], v[160:163], v[172:175], v[0:15]
	ds_read_b128 v[176:179], v207
	ds_read_b128 v[152:155], v207 offset:32
	ds_read_b128 v[188:191], v208 offset:18432
	ds_read_b128 v[156:159], v208 offset:18464
	ds_read_b128 v[184:187], v207 offset:4608
	ds_read_b128 v[160:163], v207 offset:4640
	v_mfma_f32_32x32x16_bf16 v[48:63], v[128:131], v[132:135], v[48:63]
	v_mfma_f32_32x32x16_bf16 v[16:31], v[128:131], v[140:143], v[16:31]
	ds_read_b128 v[196:199], v208 offset:23040
	ds_read_b128 v[172:175], v208 offset:23072
	ds_read_b128 v[164:167], v207 offset:64
	ds_read_b128 v[148:151], v207 offset:96
	ds_read_b128 v[168:171], v207 offset:4672
	ds_read_b128 v[128:131], v207 offset:4704
	ds_read_b128 v[180:183], v208 offset:18496
	ds_read_b128 v[144:147], v208 offset:18528
	v_mfma_f32_32x32x16_bf16 v[32:47], v[136:139], v[132:135], v[32:47]
	ds_read_b128 v[192:195], v208 offset:23104
	ds_read_b128 v[132:135], v208 offset:23136
	s_waitcnt lgkmcnt(0)
	s_barrier
	v_mfma_f32_32x32x16_bf16 v[0:15], v[136:139], v[140:143], v[0:15]
	s_cbranch_vccnz .LBB0_2046
	s_cmp_gt_u32 s17, 59
	s_waitcnt vmcnt(15)
	ds_write_b128 v206, v[80:83]
	s_waitcnt vmcnt(14)
	ds_write_b128 v206, v[84:87] offset:4608
	s_waitcnt vmcnt(13)
	ds_write_b128 v206, v[92:95] offset:9216
	s_waitcnt vmcnt(12)
	ds_write_b128 v206, v[100:103] offset:13824
	s_waitcnt vmcnt(11)
	ds_write_b128 v206, v[112:115] offset:18432
	s_waitcnt vmcnt(10)
	ds_write_b128 v206, v[116:119] offset:23040
	s_waitcnt vmcnt(9)
	ds_write_b128 v206, v[120:123] offset:27648
	s_waitcnt vmcnt(8)
	ds_write_b128 v206, v[124:127] offset:32256
	s_cbranch_scc1 .LBB0_2046
	v_lshl_add_u64 v[92:93], s[12:13], 0, v[200:201]
	v_add_co_u32_e32 v80, vcc, 0x7157000, v92
	v_lshl_add_u64 v[120:121], s[10:11], 0, v[200:201]
	s_nop 0
	v_addc_co_u32_e32 v81, vcc, 0, v93, vcc
	v_add_co_u32_e32 v84, vcc, 0x7197000, v92
	s_nop 1
	v_addc_co_u32_e32 v85, vcc, 0, v93, vcc
	v_add_co_u32_e32 v94, vcc, 0x71d7000, v92
	global_load_dwordx4 v[80:83], v[80:81], off offset:2816
	s_nop 0
	global_load_dwordx4 v[84:87], v[84:85], off offset:2816
	v_addc_co_u32_e32 v95, vcc, 0, v93, vcc
	v_add_co_u32_e32 v100, vcc, 0x7217000, v92
	s_nop 1
	v_addc_co_u32_e32 v101, vcc, 0, v93, vcc
	v_add_co_u32_e32 v112, vcc, 0xec0000, v120
	global_load_dwordx4 v[92:95], v[94:95], off offset:2816
	s_nop 0
	global_load_dwordx4 v[100:103], v[100:101], off offset:2816
	v_addc_co_u32_e32 v113, vcc, 0, v121, vcc
	v_add_co_u32_e32 v116, vcc, 0xf00000, v120
	s_nop 1
	v_addc_co_u32_e32 v117, vcc, 0, v121, vcc
	v_add_co_u32_e32 v122, vcc, 0xf40000, v120
	global_load_dwordx4 v[112:115], v[112:113], off offset:512
	s_nop 0
	global_load_dwordx4 v[116:119], v[116:117], off offset:512
	v_addc_co_u32_e32 v123, vcc, 0, v121, vcc
	v_add_co_u32_e32 v124, vcc, 0xf80000, v120
	s_nop 1
	v_addc_co_u32_e32 v125, vcc, 0, v121, vcc
	global_load_dwordx4 v[120:123], v[122:123], off offset:512
	s_nop 0
	global_load_dwordx4 v[124:127], v[124:125], off offset:512
	s_branch .LBB0_2046
